# union-3 plus: per-tile accumulator zeroing (128 v_mov) skipped for tiles that follow an epilogue; the peeled first K-iteration feeds an inline-zero C to the first MFMA of each accumulator
# speedup vs baseline: 1.0186x; 1.0081x over previous
.LBB0_182:
	s_add_u32 s57, s22, 0x100
	s_addc_u32 s59, s23, 0
	s_add_u32 s22, s24, 0x80
	v_mov_b32_e32 v0, 0
	s_addc_u32 s23, s25, 0
	s_mov_b32 s24, 0
	v_readlane_b32 s2, v246, 43
	s_cmp_lg_u32 s2, 0
	s_cbranch_scc1 .Lpeel_183
	v_mov_b32_e32 v1, v0
	v_mov_b32_e32 v2, v0
	v_mov_b32_e32 v3, v0
	v_mov_b32_e32 v4, v0
	v_mov_b32_e32 v5, v0
	v_mov_b32_e32 v6, v0
	v_mov_b32_e32 v7, v0
	v_mov_b32_e32 v8, v0
	v_mov_b32_e32 v9, v0
	v_mov_b32_e32 v10, v0
	v_mov_b32_e32 v11, v0
	v_mov_b32_e32 v16, v0
	v_mov_b32_e32 v17, v0
	v_mov_b32_e32 v18, v0
	v_mov_b32_e32 v19, v0
	v_mov_b32_e32 v24, v0
	v_mov_b32_e32 v25, v0
	v_mov_b32_e32 v26, v0
	v_mov_b32_e32 v27, v0
	v_mov_b32_e32 v32, v0
	v_mov_b32_e32 v33, v0
	v_mov_b32_e32 v34, v0
	v_mov_b32_e32 v35, v0
	v_mov_b32_e32 v48, v0
	v_mov_b32_e32 v49, v0
	v_mov_b32_e32 v50, v0
	v_mov_b32_e32 v51, v0
	v_mov_b32_e32 v52, v0
	v_mov_b32_e32 v53, v0
	v_mov_b32_e32 v54, v0
	v_mov_b32_e32 v55, v0
	v_mov_b32_e32 v12, v0
	v_mov_b32_e32 v13, v0
	v_mov_b32_e32 v14, v0
	v_mov_b32_e32 v15, v0
	v_mov_b32_e32 v20, v0
	v_mov_b32_e32 v21, v0
	v_mov_b32_e32 v22, v0
	v_mov_b32_e32 v23, v0
	v_mov_b32_e32 v28, v0
	v_mov_b32_e32 v29, v0
	v_mov_b32_e32 v30, v0
	v_mov_b32_e32 v31, v0
	v_mov_b32_e32 v36, v0
	v_mov_b32_e32 v37, v0
	v_mov_b32_e32 v38, v0
	v_mov_b32_e32 v39, v0
	v_mov_b32_e32 v40, v0
	v_mov_b32_e32 v41, v0
	v_mov_b32_e32 v42, v0
	v_mov_b32_e32 v43, v0
	v_mov_b32_e32 v44, v0
	v_mov_b32_e32 v45, v0
	v_mov_b32_e32 v46, v0
	v_mov_b32_e32 v47, v0
	v_mov_b32_e32 v56, v0
	v_mov_b32_e32 v57, v0
	v_mov_b32_e32 v58, v0
	v_mov_b32_e32 v59, v0
	v_mov_b32_e32 v60, v0
	v_mov_b32_e32 v61, v0
	v_mov_b32_e32 v62, v0
	v_mov_b32_e32 v63, v0
	v_mov_b32_e32 v64, v0
	v_mov_b32_e32 v65, v0
	v_mov_b32_e32 v66, v0
	v_mov_b32_e32 v67, v0
	v_mov_b32_e32 v68, v0
	v_mov_b32_e32 v69, v0
	v_mov_b32_e32 v70, v0
	v_mov_b32_e32 v71, v0
	v_mov_b32_e32 v72, v0
	v_mov_b32_e32 v73, v0
	v_mov_b32_e32 v74, v0
	v_mov_b32_e32 v75, v0
	v_mov_b32_e32 v84, v0
	v_mov_b32_e32 v85, v0
	v_mov_b32_e32 v86, v0
	v_mov_b32_e32 v87, v0
	v_mov_b32_e32 v96, v0
	v_mov_b32_e32 v97, v0
	v_mov_b32_e32 v98, v0
	v_mov_b32_e32 v99, v0
	v_mov_b32_e32 v100, v0
	v_mov_b32_e32 v101, v0
	v_mov_b32_e32 v102, v0
	v_mov_b32_e32 v103, v0
	v_mov_b32_e32 v128, v0
	v_mov_b32_e32 v129, v0
	v_mov_b32_e32 v130, v0
	v_mov_b32_e32 v131, v0
	v_mov_b32_e32 v132, v0
	v_mov_b32_e32 v133, v0
	v_mov_b32_e32 v134, v0
	v_mov_b32_e32 v135, v0
	v_mov_b32_e32 v76, v0
	v_mov_b32_e32 v77, v0
	v_mov_b32_e32 v78, v0
	v_mov_b32_e32 v79, v0
	v_mov_b32_e32 v80, v0
	v_mov_b32_e32 v81, v0
	v_mov_b32_e32 v82, v0
	v_mov_b32_e32 v83, v0
	v_mov_b32_e32 v88, v0
	v_mov_b32_e32 v89, v0
	v_mov_b32_e32 v90, v0
	v_mov_b32_e32 v91, v0
	v_mov_b32_e32 v92, v0
	v_mov_b32_e32 v93, v0
	v_mov_b32_e32 v94, v0
	v_mov_b32_e32 v95, v0
	v_mov_b32_e32 v120, v0
	v_mov_b32_e32 v121, v0
	v_mov_b32_e32 v122, v0
	v_mov_b32_e32 v123, v0
	v_mov_b32_e32 v124, v0
	v_mov_b32_e32 v125, v0
	v_mov_b32_e32 v126, v0
	v_mov_b32_e32 v127, v0
	v_mov_b32_e32 v136, v0
	v_mov_b32_e32 v137, v0
	v_mov_b32_e32 v138, v0
	v_mov_b32_e32 v139, v0
	v_mov_b32_e32 v140, v0
	v_mov_b32_e32 v141, v0
	v_mov_b32_e32 v142, v0
	v_mov_b32_e32 v143, v0
	s_branch .LBB0_183
.Lpeel_183:
	s_add_i32 s60, s24, 2
	s_add_u32 s2, s22, 0x80
	s_addc_u32 s3, s23, 0
	s_add_i32 s61, 0, 0x10000
	s_cmp_eq_u32 s51, s24
	s_cselect_b32 s25, s1, s3
	s_cselect_b32 s24, s0, s2
	s_cselect_b32 s3, s21, s59
	s_cselect_b32 s2, s20, s57
	s_add_i32 s62, 0, 0x14000
	v_add_u32_e32 v116, s61, v192
	v_add_u32_e32 v156, s62, v192
	ds_read_b128 v[104:107], v116
	ds_read_b128 v[108:111], v116 offset:1024
	ds_read_b128 v[112:115], v116 offset:2048
	ds_read_b128 v[116:119], v116 offset:3072
	ds_read_b128 v[144:147], v156
	ds_read_b128 v[148:151], v156 offset:1024
	ds_read_b128 v[152:155], v156 offset:2048
	ds_read_b128 v[156:159], v156 offset:3072
	v_lshl_add_u64 v[190:191], s[22:23], 0, v[188:189]
	s_add_i32 m0, s31, 0xc000
	ds_read_b128 v[160:163], v194
	ds_read_b128 v[164:167], v194 offset:1024
	ds_read_b128 v[196:199], v194 offset:2048
	ds_read_b128 v[200:203], v194 offset:3072
	ds_read_b128 v[210:213], v194 offset:4096
	ds_read_b128 v[214:217], v194 offset:5120
	ds_read_b128 v[218:221], v194 offset:6144
	ds_read_b128 v[222:225], v194 offset:7168
	global_load_lds_dwordx4 v[190:191], off
	v_lshl_add_u64 v[190:191], s[22:23], 0, v[186:187]
	s_add_i32 m0, s31, 0xe000
	s_nop 0
	global_load_lds_dwordx4 v[190:191], off
	s_waitcnt vmcnt(40)
	s_waitcnt lgkmcnt(0)
	s_setprio 1
	s_barrier
	v_mfma_f32_16x16x32_bf16 v[140:143], v[104:107], v[160:163], 0
	v_mfma_f32_16x16x32_bf16 v[140:143], v[108:111], v[164:167], v[140:143]
	v_mfma_f32_16x16x32_bf16 v[136:139], v[112:115], v[160:163], 0
	v_mfma_f32_16x16x32_bf16 v[136:139], v[116:119], v[164:167], v[136:139]
	v_mfma_f32_16x16x32_bf16 v[124:127], v[104:107], v[196:199], 0
	v_mfma_f32_16x16x32_bf16 v[124:127], v[108:111], v[200:203], v[124:127]
	v_mfma_f32_16x16x32_bf16 v[120:123], v[112:115], v[196:199], 0
	v_mfma_f32_16x16x32_bf16 v[120:123], v[116:119], v[200:203], v[120:123]
	v_mfma_f32_16x16x32_bf16 v[92:95], v[104:107], v[210:213], 0
	v_mfma_f32_16x16x32_bf16 v[92:95], v[108:111], v[214:217], v[92:95]
	v_mfma_f32_16x16x32_bf16 v[88:91], v[112:115], v[210:213], 0
	v_mfma_f32_16x16x32_bf16 v[88:91], v[116:119], v[214:217], v[88:91]
	v_mfma_f32_16x16x32_bf16 v[80:83], v[104:107], v[218:221], 0
	v_mfma_f32_16x16x32_bf16 v[80:83], v[108:111], v[222:225], v[80:83]
	v_mfma_f32_16x16x32_bf16 v[76:79], v[112:115], v[218:221], 0
	v_mfma_f32_16x16x32_bf16 v[76:79], v[116:119], v[222:225], v[76:79]
	v_mfma_f32_16x16x32_bf16 v[132:135], v[144:147], v[160:163], 0
	v_mfma_f32_16x16x32_bf16 v[132:135], v[148:151], v[164:167], v[132:135]
	v_mfma_f32_16x16x32_bf16 v[128:131], v[152:155], v[160:163], 0
	v_mfma_f32_16x16x32_bf16 v[128:131], v[156:159], v[164:167], v[128:131]
	v_mfma_f32_16x16x32_bf16 v[100:103], v[144:147], v[196:199], 0
	v_mfma_f32_16x16x32_bf16 v[100:103], v[148:151], v[200:203], v[100:103]
	v_mfma_f32_16x16x32_bf16 v[96:99], v[152:155], v[196:199], 0
	v_mfma_f32_16x16x32_bf16 v[96:99], v[156:159], v[200:203], v[96:99]
	v_mfma_f32_16x16x32_bf16 v[84:87], v[144:147], v[210:213], 0
	v_mfma_f32_16x16x32_bf16 v[84:87], v[148:151], v[214:217], v[84:87]
	v_mfma_f32_16x16x32_bf16 v[72:75], v[152:155], v[210:213], 0
	v_mfma_f32_16x16x32_bf16 v[72:75], v[156:159], v[214:217], v[72:75]
	v_mfma_f32_16x16x32_bf16 v[68:71], v[144:147], v[218:221], 0
	v_mfma_f32_16x16x32_bf16 v[68:71], v[148:151], v[222:225], v[68:71]
	s_setprio 3
	s_barrier
	v_mfma_f32_16x16x32_bf16 v[64:67], v[152:155], v[218:221], 0
	v_mfma_f32_16x16x32_bf16 v[64:67], v[156:159], v[222:225], v[64:67]
	s_setprio 0
	s_add_i32 s61, s61, s30
	v_lshl_add_u64 v[190:191], s[2:3], 0, v[174:175]
	s_mov_b32 m0, s61
	ds_read_b128 v[160:163], v194 offset:16384
	ds_read_b128 v[164:167], v194 offset:17408
	ds_read_b128 v[196:199], v194 offset:18432
	ds_read_b128 v[200:203], v194 offset:19456
	ds_read_b128 v[210:213], v194 offset:20480
	ds_read_b128 v[214:217], v194 offset:21504
	ds_read_b128 v[218:221], v194 offset:22528
	ds_read_b128 v[222:225], v194 offset:23552
	global_load_lds_dwordx4 v[190:191], off
	s_add_i32 m0, s61, 0x2000
	v_lshl_add_u64 v[226:227], s[2:3], 0, v[184:185]
	s_add_u32 s2, s2, s27
	s_addc_u32 s3, s3, 0
	s_add_i32 s61, s62, s30
	global_load_lds_dwordx4 v[226:227], off
	v_lshl_add_u64 v[228:229], s[2:3], 0, v[174:175]
	s_mov_b32 m0, s61
	v_lshl_add_u64 v[230:231], s[2:3], 0, v[184:185]
	global_load_lds_dwordx4 v[228:229], off
	s_add_i32 m0, s61, 0x2000
	v_lshl_add_u64 v[232:233], s[24:25], 0, v[168:169]
	global_load_lds_dwordx4 v[230:231], off
	s_mov_b32 m0, s31
	v_lshl_add_u64 v[234:235], s[24:25], 0, v[170:171]
	global_load_lds_dwordx4 v[232:233], off
	s_mov_b32 m0, s34
	s_nop 0
	global_load_lds_dwordx4 v[234:235], off
	s_waitcnt vmcnt(40)
	s_waitcnt lgkmcnt(0)
	s_setprio 1
	s_barrier
	v_mfma_f32_16x16x32_bf16 v[60:63], v[104:107], v[160:163], 0
	v_mfma_f32_16x16x32_bf16 v[60:63], v[108:111], v[164:167], v[60:63]
	v_mfma_f32_16x16x32_bf16 v[56:59], v[112:115], v[160:163], 0
	v_mfma_f32_16x16x32_bf16 v[56:59], v[116:119], v[164:167], v[56:59]
	v_mfma_f32_16x16x32_bf16 v[44:47], v[104:107], v[196:199], 0
	v_mfma_f32_16x16x32_bf16 v[44:47], v[108:111], v[200:203], v[44:47]
	v_mfma_f32_16x16x32_bf16 v[40:43], v[112:115], v[196:199], 0
	v_mfma_f32_16x16x32_bf16 v[40:43], v[116:119], v[200:203], v[40:43]
	v_mfma_f32_16x16x32_bf16 v[36:39], v[104:107], v[210:213], 0
	v_mfma_f32_16x16x32_bf16 v[36:39], v[108:111], v[214:217], v[36:39]
	v_mfma_f32_16x16x32_bf16 v[28:31], v[112:115], v[210:213], 0
	v_mfma_f32_16x16x32_bf16 v[28:31], v[116:119], v[214:217], v[28:31]
	v_mfma_f32_16x16x32_bf16 v[20:23], v[104:107], v[218:221], 0
	v_mfma_f32_16x16x32_bf16 v[20:23], v[108:111], v[222:225], v[20:23]
	v_mfma_f32_16x16x32_bf16 v[12:15], v[112:115], v[218:221], 0
	v_mfma_f32_16x16x32_bf16 v[12:15], v[116:119], v[222:225], v[12:15]
	v_mfma_f32_16x16x32_bf16 v[52:55], v[144:147], v[160:163], 0
	v_mfma_f32_16x16x32_bf16 v[52:55], v[148:151], v[164:167], v[52:55]
	v_mfma_f32_16x16x32_bf16 v[48:51], v[152:155], v[160:163], 0
	v_mfma_f32_16x16x32_bf16 v[48:51], v[156:159], v[164:167], v[48:51]
	v_mfma_f32_16x16x32_bf16 v[32:35], v[144:147], v[196:199], 0
	v_mfma_f32_16x16x32_bf16 v[32:35], v[148:151], v[200:203], v[32:35]
	v_mfma_f32_16x16x32_bf16 v[24:27], v[152:155], v[196:199], 0
	v_mfma_f32_16x16x32_bf16 v[24:27], v[156:159], v[200:203], v[24:27]
	v_mfma_f32_16x16x32_bf16 v[16:19], v[144:147], v[210:213], 0
	v_mfma_f32_16x16x32_bf16 v[16:19], v[148:151], v[214:217], v[16:19]
	v_mfma_f32_16x16x32_bf16 v[8:11], v[152:155], v[210:213], 0
	v_mfma_f32_16x16x32_bf16 v[8:11], v[156:159], v[214:217], v[8:11]
	v_mfma_f32_16x16x32_bf16 v[4:7], v[144:147], v[218:221], 0
	v_mfma_f32_16x16x32_bf16 v[4:7], v[148:151], v[222:225], v[4:7]
	s_setprio 3
	s_barrier
	v_mfma_f32_16x16x32_bf16 v[0:3], v[152:155], v[218:221], 0
	v_mfma_f32_16x16x32_bf16 v[0:3], v[156:159], v[222:225], v[0:3]
	s_setprio 0
	s_add_i32 s61, 0, 0x18000
	s_add_i32 s62, 0, 0x1c000
	v_add_u32_e32 v116, s61, v192
	v_add_u32_e32 v156, s62, v192
	ds_read_b128 v[104:107], v116
	ds_read_b128 v[108:111], v116 offset:1024
	ds_read_b128 v[112:115], v116 offset:2048
	ds_read_b128 v[116:119], v116 offset:3072
	ds_read_b128 v[144:147], v156
	ds_read_b128 v[148:151], v156 offset:1024
	ds_read_b128 v[152:155], v156 offset:2048
	ds_read_b128 v[156:159], v156 offset:3072
	s_add_u32 s2, s24, s78
	s_addc_u32 s3, s25, 0
	s_mov_b32 m0, s35
	v_lshl_add_u64 v[236:237], s[2:3], 0, v[168:169]
	ds_read_b128 v[160:163], v194 offset:32768
	ds_read_b128 v[164:167], v194 offset:33792
	ds_read_b128 v[196:199], v194 offset:34816
	ds_read_b128 v[200:203], v194 offset:35840
	ds_read_b128 v[210:213], v194 offset:36864
	ds_read_b128 v[214:217], v194 offset:37888
	ds_read_b128 v[218:221], v194 offset:38912
	ds_read_b128 v[222:225], v194 offset:39936
	global_load_lds_dwordx4 v[236:237], off
	v_lshl_add_u64 v[236:237], s[2:3], 0, v[170:171]
	s_mov_b32 m0, s36
	s_nop 0
	global_load_lds_dwordx4 v[236:237], off
	s_waitcnt vmcnt(8)
	s_waitcnt lgkmcnt(0)
	s_setprio 1
	s_barrier
	v_mfma_f32_16x16x32_bf16 v[140:143], v[104:107], v[160:163], v[140:143]
	v_mfma_f32_16x16x32_bf16 v[140:143], v[108:111], v[164:167], v[140:143]
	v_mfma_f32_16x16x32_bf16 v[136:139], v[112:115], v[160:163], v[136:139]
	v_mfma_f32_16x16x32_bf16 v[136:139], v[116:119], v[164:167], v[136:139]
	v_mfma_f32_16x16x32_bf16 v[124:127], v[104:107], v[196:199], v[124:127]
	v_mfma_f32_16x16x32_bf16 v[124:127], v[108:111], v[200:203], v[124:127]
	v_mfma_f32_16x16x32_bf16 v[120:123], v[112:115], v[196:199], v[120:123]
	v_mfma_f32_16x16x32_bf16 v[120:123], v[116:119], v[200:203], v[120:123]
	v_mfma_f32_16x16x32_bf16 v[92:95], v[104:107], v[210:213], v[92:95]
	v_mfma_f32_16x16x32_bf16 v[92:95], v[108:111], v[214:217], v[92:95]
	v_mfma_f32_16x16x32_bf16 v[88:91], v[112:115], v[210:213], v[88:91]
	v_mfma_f32_16x16x32_bf16 v[88:91], v[116:119], v[214:217], v[88:91]
	v_mfma_f32_16x16x32_bf16 v[80:83], v[104:107], v[218:221], v[80:83]
	v_mfma_f32_16x16x32_bf16 v[80:83], v[108:111], v[222:225], v[80:83]
	v_mfma_f32_16x16x32_bf16 v[76:79], v[112:115], v[218:221], v[76:79]
	v_mfma_f32_16x16x32_bf16 v[76:79], v[116:119], v[222:225], v[76:79]
	v_mfma_f32_16x16x32_bf16 v[132:135], v[144:147], v[160:163], v[132:135]
	v_mfma_f32_16x16x32_bf16 v[132:135], v[148:151], v[164:167], v[132:135]
	v_mfma_f32_16x16x32_bf16 v[128:131], v[152:155], v[160:163], v[128:131]
	v_mfma_f32_16x16x32_bf16 v[128:131], v[156:159], v[164:167], v[128:131]
	v_mfma_f32_16x16x32_bf16 v[100:103], v[144:147], v[196:199], v[100:103]
	v_mfma_f32_16x16x32_bf16 v[100:103], v[148:151], v[200:203], v[100:103]
	v_mfma_f32_16x16x32_bf16 v[96:99], v[152:155], v[196:199], v[96:99]
	v_mfma_f32_16x16x32_bf16 v[96:99], v[156:159], v[200:203], v[96:99]
	v_mfma_f32_16x16x32_bf16 v[84:87], v[144:147], v[210:213], v[84:87]
	v_mfma_f32_16x16x32_bf16 v[84:87], v[148:151], v[214:217], v[84:87]
	v_mfma_f32_16x16x32_bf16 v[72:75], v[152:155], v[210:213], v[72:75]
	v_mfma_f32_16x16x32_bf16 v[72:75], v[156:159], v[214:217], v[72:75]
	v_mfma_f32_16x16x32_bf16 v[68:71], v[144:147], v[218:221], v[68:71]
	v_mfma_f32_16x16x32_bf16 v[68:71], v[148:151], v[222:225], v[68:71]
	s_setprio 3
	s_barrier
	v_mfma_f32_16x16x32_bf16 v[64:67], v[152:155], v[218:221], v[64:67]
	v_mfma_f32_16x16x32_bf16 v[64:67], v[156:159], v[222:225], v[64:67]
	s_setprio 0
	s_add_i32 s2, s61, s30
	v_lshl_add_u64 v[190:191], v[190:191], 0, s[82:83]
	s_mov_b32 m0, s2
	ds_read_b128 v[160:163], v194 offset:49152
	ds_read_b128 v[164:167], v194 offset:50176
	ds_read_b128 v[196:199], v194 offset:51200
	ds_read_b128 v[200:203], v194 offset:52224
	ds_read_b128 v[210:213], v194 offset:53248
	ds_read_b128 v[214:217], v194 offset:54272
	ds_read_b128 v[218:221], v194 offset:55296
	ds_read_b128 v[222:225], v194 offset:56320
	global_load_lds_dwordx4 v[190:191], off
	v_lshl_add_u64 v[190:191], v[226:227], 0, s[82:83]
	s_add_i32 m0, s2, 0x2000
	s_add_i32 s2, s62, s30
	global_load_lds_dwordx4 v[190:191], off
	v_lshl_add_u64 v[190:191], v[228:229], 0, s[82:83]
	s_mov_b32 m0, s2
	s_nop 0
	global_load_lds_dwordx4 v[190:191], off
	v_lshl_add_u64 v[190:191], v[230:231], 0, s[82:83]
	s_add_i32 m0, s2, 0x2000
	s_nop 0
	global_load_lds_dwordx4 v[190:191], off
	v_lshl_add_u64 v[190:191], v[232:233], 0, s[82:83]
	s_mov_b32 m0, s47
	s_nop 0
	global_load_lds_dwordx4 v[190:191], off
	v_lshl_add_u64 v[190:191], v[234:235], 0, s[82:83]
	s_mov_b32 m0, s50
	s_nop 0
	global_load_lds_dwordx4 v[190:191], off
	s_waitcnt vmcnt(8)
	s_waitcnt lgkmcnt(0)
	s_setprio 1
	s_barrier
	v_mfma_f32_16x16x32_bf16 v[60:63], v[104:107], v[160:163], v[60:63]
	v_mfma_f32_16x16x32_bf16 v[60:63], v[108:111], v[164:167], v[60:63]
	v_mfma_f32_16x16x32_bf16 v[56:59], v[112:115], v[160:163], v[56:59]
	v_mfma_f32_16x16x32_bf16 v[56:59], v[116:119], v[164:167], v[56:59]
	v_mfma_f32_16x16x32_bf16 v[44:47], v[104:107], v[196:199], v[44:47]
	v_mfma_f32_16x16x32_bf16 v[44:47], v[108:111], v[200:203], v[44:47]
	v_mfma_f32_16x16x32_bf16 v[40:43], v[112:115], v[196:199], v[40:43]
	v_mfma_f32_16x16x32_bf16 v[40:43], v[116:119], v[200:203], v[40:43]
	v_mfma_f32_16x16x32_bf16 v[36:39], v[104:107], v[210:213], v[36:39]
	v_mfma_f32_16x16x32_bf16 v[36:39], v[108:111], v[214:217], v[36:39]
	v_mfma_f32_16x16x32_bf16 v[28:31], v[112:115], v[210:213], v[28:31]
	v_mfma_f32_16x16x32_bf16 v[28:31], v[116:119], v[214:217], v[28:31]
	v_mfma_f32_16x16x32_bf16 v[20:23], v[104:107], v[218:221], v[20:23]
	v_mfma_f32_16x16x32_bf16 v[20:23], v[108:111], v[222:225], v[20:23]
	v_mfma_f32_16x16x32_bf16 v[12:15], v[112:115], v[218:221], v[12:15]
	v_mfma_f32_16x16x32_bf16 v[12:15], v[116:119], v[222:225], v[12:15]
	v_mfma_f32_16x16x32_bf16 v[52:55], v[144:147], v[160:163], v[52:55]
	v_mfma_f32_16x16x32_bf16 v[52:55], v[148:151], v[164:167], v[52:55]
	v_mfma_f32_16x16x32_bf16 v[48:51], v[152:155], v[160:163], v[48:51]
	v_mfma_f32_16x16x32_bf16 v[48:51], v[156:159], v[164:167], v[48:51]
	v_mfma_f32_16x16x32_bf16 v[32:35], v[144:147], v[196:199], v[32:35]
	v_mfma_f32_16x16x32_bf16 v[32:35], v[148:151], v[200:203], v[32:35]
	v_mfma_f32_16x16x32_bf16 v[24:27], v[152:155], v[196:199], v[24:27]
	v_mfma_f32_16x16x32_bf16 v[24:27], v[156:159], v[200:203], v[24:27]
	v_mfma_f32_16x16x32_bf16 v[16:19], v[144:147], v[210:213], v[16:19]
	v_mfma_f32_16x16x32_bf16 v[16:19], v[148:151], v[214:217], v[16:19]
	v_mfma_f32_16x16x32_bf16 v[8:11], v[152:155], v[210:213], v[8:11]
	v_mfma_f32_16x16x32_bf16 v[8:11], v[156:159], v[214:217], v[8:11]
	v_mfma_f32_16x16x32_bf16 v[4:7], v[144:147], v[218:221], v[4:7]
	v_mfma_f32_16x16x32_bf16 v[4:7], v[148:151], v[222:225], v[4:7]
	s_setprio 3
	s_barrier
	v_mfma_f32_16x16x32_bf16 v[0:3], v[152:155], v[218:221], v[0:3]
	v_mfma_f32_16x16x32_bf16 v[0:3], v[156:159], v[222:225], v[0:3]
	s_setprio 0
	s_add_u32 s57, s57, 0x100
	s_addc_u32 s59, s59, 0
	s_add_u32 s22, s22, 0x100
	s_addc_u32 s23, s23, 0
	s_cmp_ge_u32 s60, s46
	s_mov_b32 s24, s60
	s_cbranch_scc1 .Lexit_183

.LBB0_241:
	s_ashr_i32 s35, s34, 31
	s_lshl_b64 s[12:13], s[34:35], 19
	s_add_u32 s36, s40, s12
	s_addc_u32 s37, s41, s13
	s_and_b64 s[12:13], s[4:5], exec
	s_cselect_b32 s7, s37, s11
	s_cselect_b32 s35, s36, s10
	s_ashr_i32 s31, s30, 31
	s_lshl_b64 s[12:13], s[30:31], 19
	s_add_u32 s50, s42, s12
	s_addc_u32 s51, s43, s13
	s_and_b64 s[12:13], s[4:5], exec
	s_cselect_b32 s31, s51, s9
	s_cselect_b32 s89, s50, s8
	s_add_u32 vcc_lo, s8, 0x100
	s_addc_u32 vcc_hi, s9, 0
	s_add_u32 s8, s10, 0x40080
	v_mov_b32_e32 v0, 0
	s_addc_u32 s9, s11, 0
	s_mov_b32 s12, -2
	v_readlane_b32 s2, v246, 42
	s_cmp_lg_u32 s2, 0
	s_cbranch_scc1 .Lpeel_242
	v_mov_b32_e32 v1, v0
	v_mov_b32_e32 v2, v0
	v_mov_b32_e32 v3, v0
	v_mov_b32_e32 v4, v0
	v_mov_b32_e32 v5, v0
	v_mov_b32_e32 v6, v0
	v_mov_b32_e32 v7, v0
	v_mov_b32_e32 v16, v0
	v_mov_b32_e32 v17, v0
	v_mov_b32_e32 v18, v0
	v_mov_b32_e32 v19, v0
	v_mov_b32_e32 v20, v0
	v_mov_b32_e32 v21, v0
	v_mov_b32_e32 v22, v0
	v_mov_b32_e32 v23, v0
	v_mov_b32_e32 v32, v0
	v_mov_b32_e32 v33, v0
	v_mov_b32_e32 v34, v0
	v_mov_b32_e32 v35, v0
	v_mov_b32_e32 v36, v0
	v_mov_b32_e32 v37, v0
	v_mov_b32_e32 v38, v0
	v_mov_b32_e32 v39, v0
	v_mov_b32_e32 v48, v0
	v_mov_b32_e32 v49, v0
	v_mov_b32_e32 v50, v0
	v_mov_b32_e32 v51, v0
	v_mov_b32_e32 v52, v0
	v_mov_b32_e32 v53, v0
	v_mov_b32_e32 v54, v0
	v_mov_b32_e32 v55, v0
	v_mov_b32_e32 v8, v0
	v_mov_b32_e32 v9, v0
	v_mov_b32_e32 v10, v0
	v_mov_b32_e32 v11, v0
	v_mov_b32_e32 v12, v0
	v_mov_b32_e32 v13, v0
	v_mov_b32_e32 v14, v0
	v_mov_b32_e32 v15, v0
	v_mov_b32_e32 v24, v0
	v_mov_b32_e32 v25, v0
	v_mov_b32_e32 v26, v0
	v_mov_b32_e32 v27, v0
	v_mov_b32_e32 v28, v0
	v_mov_b32_e32 v29, v0
	v_mov_b32_e32 v30, v0
	v_mov_b32_e32 v31, v0
	v_mov_b32_e32 v40, v0
	v_mov_b32_e32 v41, v0
	v_mov_b32_e32 v42, v0
	v_mov_b32_e32 v43, v0
	v_mov_b32_e32 v44, v0
	v_mov_b32_e32 v45, v0
	v_mov_b32_e32 v46, v0
	v_mov_b32_e32 v47, v0
	v_mov_b32_e32 v56, v0
	v_mov_b32_e32 v57, v0
	v_mov_b32_e32 v58, v0
	v_mov_b32_e32 v59, v0
	v_mov_b32_e32 v60, v0
	v_mov_b32_e32 v61, v0
	v_mov_b32_e32 v62, v0
	v_mov_b32_e32 v63, v0
	v_mov_b32_e32 v64, v0
	v_mov_b32_e32 v65, v0
	v_mov_b32_e32 v66, v0
	v_mov_b32_e32 v67, v0
	v_mov_b32_e32 v68, v0
	v_mov_b32_e32 v69, v0
	v_mov_b32_e32 v70, v0
	v_mov_b32_e32 v71, v0
	v_mov_b32_e32 v80, v0
	v_mov_b32_e32 v81, v0
	v_mov_b32_e32 v82, v0
	v_mov_b32_e32 v83, v0
	v_mov_b32_e32 v84, v0
	v_mov_b32_e32 v85, v0
	v_mov_b32_e32 v86, v0
	v_mov_b32_e32 v87, v0
	v_mov_b32_e32 v96, v0
	v_mov_b32_e32 v97, v0
	v_mov_b32_e32 v98, v0
	v_mov_b32_e32 v99, v0
	v_mov_b32_e32 v100, v0
	v_mov_b32_e32 v101, v0
	v_mov_b32_e32 v102, v0
	v_mov_b32_e32 v103, v0
	v_mov_b32_e32 v112, v0
	v_mov_b32_e32 v113, v0
	v_mov_b32_e32 v114, v0
	v_mov_b32_e32 v115, v0
	v_mov_b32_e32 v116, v0
	v_mov_b32_e32 v117, v0
	v_mov_b32_e32 v118, v0
	v_mov_b32_e32 v119, v0
	v_mov_b32_e32 v72, v0
	v_mov_b32_e32 v73, v0
	v_mov_b32_e32 v74, v0
	v_mov_b32_e32 v75, v0
	v_mov_b32_e32 v76, v0
	v_mov_b32_e32 v77, v0
	v_mov_b32_e32 v78, v0
	v_mov_b32_e32 v79, v0
	v_mov_b32_e32 v88, v0
	v_mov_b32_e32 v89, v0
	v_mov_b32_e32 v90, v0
	v_mov_b32_e32 v91, v0
	v_mov_b32_e32 v92, v0
	v_mov_b32_e32 v93, v0
	v_mov_b32_e32 v94, v0
	v_mov_b32_e32 v95, v0
	v_mov_b32_e32 v104, v0
	v_mov_b32_e32 v105, v0
	v_mov_b32_e32 v106, v0
	v_mov_b32_e32 v107, v0
	v_mov_b32_e32 v108, v0
	v_mov_b32_e32 v109, v0
	v_mov_b32_e32 v110, v0
	v_mov_b32_e32 v111, v0
	v_mov_b32_e32 v120, v0
	v_mov_b32_e32 v121, v0
	v_mov_b32_e32 v122, v0
	v_mov_b32_e32 v123, v0
	v_mov_b32_e32 v124, v0
	v_mov_b32_e32 v125, v0
	v_mov_b32_e32 v126, v0
	v_mov_b32_e32 v127, v0
	s_branch .LBB0_242
.Lpeel_242:
	s_add_u32 s2, s8, 0xfffc0080
	s_addc_u32 s3, s9, -1
	s_add_i32 s13, 0, 0x10000
	s_cmp_eq_u32 s12, 12
	s_cselect_b32 s53, s7, s3
	s_cselect_b32 s52, s35, s2
	v_add_u32_e32 v156, s13, v164
	s_cselect_b32 s11, s31, vcc_hi
	s_cselect_b32 s10, s89, vcc_lo
	s_add_i32 s77, 0, 0x14000
	ds_read_b128 v[144:147], v156
	ds_read_b128 v[148:151], v156 offset:1024
	ds_read_b128 v[152:155], v156 offset:2048
	ds_read_b128 v[166:169], v156 offset:3072
	v_add_u32_e32 v156, s77, v164
	ds_read_b128 v[184:187], v156
	ds_read_b128 v[188:191], v156 offset:1024
	ds_read_b128 v[192:195], v156 offset:2048
	ds_read_b128 v[196:199], v156 offset:3072
	v_lshl_add_u64 v[156:157], s[8:9], 0, v[142:143]
	s_add_i32 m0, s19, 0xc000
	ds_read_b128 v[200:203], v165
	ds_read_b128 v[210:213], v165 offset:1024
	ds_read_b128 v[214:217], v165 offset:2048
	ds_read_b128 v[218:221], v165 offset:3072
	ds_read_b128 v[222:225], v165 offset:4096
	ds_read_b128 v[226:229], v165 offset:5120
	ds_read_b128 v[230:233], v165 offset:6144
	ds_read_b128 v[234:237], v165 offset:7168
	global_load_lds_dwordx4 v[156:157], off
	v_lshl_add_u64 v[156:157], s[8:9], 0, v[140:141]
	s_add_i32 m0, s19, 0xe000
	s_nop 0
	global_load_lds_dwordx4 v[156:157], off
	s_waitcnt vmcnt(24)
	s_waitcnt lgkmcnt(0)
	s_setprio 1
	s_barrier
	v_mfma_f32_16x16x32_bf16 v[124:127], v[144:147], v[200:203], 0
	v_mfma_f32_16x16x32_bf16 v[124:127], v[148:151], v[210:213], v[124:127]
	v_mfma_f32_16x16x32_bf16 v[120:123], v[152:155], v[200:203], 0
	v_mfma_f32_16x16x32_bf16 v[120:123], v[166:169], v[210:213], v[120:123]
	v_mfma_f32_16x16x32_bf16 v[108:111], v[144:147], v[214:217], 0
	v_mfma_f32_16x16x32_bf16 v[108:111], v[148:151], v[218:221], v[108:111]
	v_mfma_f32_16x16x32_bf16 v[104:107], v[152:155], v[214:217], 0
	v_mfma_f32_16x16x32_bf16 v[104:107], v[166:169], v[218:221], v[104:107]
	v_mfma_f32_16x16x32_bf16 v[92:95], v[144:147], v[222:225], 0
	v_mfma_f32_16x16x32_bf16 v[92:95], v[148:151], v[226:229], v[92:95]
	v_mfma_f32_16x16x32_bf16 v[88:91], v[152:155], v[222:225], 0
	v_mfma_f32_16x16x32_bf16 v[88:91], v[166:169], v[226:229], v[88:91]
	v_mfma_f32_16x16x32_bf16 v[76:79], v[144:147], v[230:233], 0
	v_mfma_f32_16x16x32_bf16 v[76:79], v[148:151], v[234:237], v[76:79]
	v_mfma_f32_16x16x32_bf16 v[72:75], v[152:155], v[230:233], 0
	v_mfma_f32_16x16x32_bf16 v[72:75], v[166:169], v[234:237], v[72:75]
	v_mfma_f32_16x16x32_bf16 v[116:119], v[184:187], v[200:203], 0
	v_mfma_f32_16x16x32_bf16 v[116:119], v[188:191], v[210:213], v[116:119]
	v_mfma_f32_16x16x32_bf16 v[112:115], v[192:195], v[200:203], 0
	v_mfma_f32_16x16x32_bf16 v[112:115], v[196:199], v[210:213], v[112:115]
	v_mfma_f32_16x16x32_bf16 v[100:103], v[184:187], v[214:217], 0
	v_mfma_f32_16x16x32_bf16 v[100:103], v[188:191], v[218:221], v[100:103]
	v_mfma_f32_16x16x32_bf16 v[96:99], v[192:195], v[214:217], 0
	v_mfma_f32_16x16x32_bf16 v[96:99], v[196:199], v[218:221], v[96:99]
	v_mfma_f32_16x16x32_bf16 v[84:87], v[184:187], v[222:225], 0
	v_mfma_f32_16x16x32_bf16 v[84:87], v[188:191], v[226:229], v[84:87]
	v_mfma_f32_16x16x32_bf16 v[80:83], v[192:195], v[222:225], 0
	v_mfma_f32_16x16x32_bf16 v[80:83], v[196:199], v[226:229], v[80:83]
	v_mfma_f32_16x16x32_bf16 v[68:71], v[184:187], v[230:233], 0
	v_mfma_f32_16x16x32_bf16 v[68:71], v[188:191], v[234:237], v[68:71]
	s_setprio 3
	s_barrier
	v_mfma_f32_16x16x32_bf16 v[64:67], v[192:195], v[230:233], 0
	v_mfma_f32_16x16x32_bf16 v[64:67], v[196:199], v[234:237], v[64:67]
	s_setprio 0
	s_add_i32 s2, s13, s56
	v_lshl_add_u64 v[156:157], s[10:11], 0, v[174:175]
	s_mov_b32 m0, s2
	ds_read_b128 v[200:203], v165 offset:16384
	ds_read_b128 v[210:213], v165 offset:17408
	ds_read_b128 v[214:217], v165 offset:18432
	ds_read_b128 v[218:221], v165 offset:19456
	ds_read_b128 v[222:225], v165 offset:20480
	ds_read_b128 v[226:229], v165 offset:21504
	ds_read_b128 v[230:233], v165 offset:22528
	ds_read_b128 v[234:237], v165 offset:23552
	global_load_lds_dwordx4 v[156:157], off
	s_add_i32 m0, s2, 0x2000
	s_add_u32 s2, s10, 0x40000
	v_lshl_add_u64 v[170:171], s[10:11], 0, v[132:133]
	s_addc_u32 s3, s11, 0
	s_add_i32 s13, s77, s56
	global_load_lds_dwordx4 v[170:171], off
	v_lshl_add_u64 v[238:239], s[2:3], 0, v[174:175]
	s_mov_b32 m0, s13
	v_lshl_add_u64 v[240:241], s[52:53], 0, v[130:131]
	global_load_lds_dwordx4 v[238:239], off
	v_lshl_add_u64 v[238:239], s[2:3], 0, v[132:133]
	s_add_i32 m0, s13, 0x2000
	s_nop 0
	global_load_lds_dwordx4 v[238:239], off
	v_lshl_add_u64 v[238:239], s[52:53], 0, v[128:129]
	s_mov_b32 m0, s19
	s_nop 0
	global_load_lds_dwordx4 v[238:239], off
	s_mov_b32 m0, s57
	s_nop 0
	global_load_lds_dwordx4 v[240:241], off
	s_waitcnt vmcnt(24)
	s_waitcnt lgkmcnt(0)
	s_setprio 1
	s_barrier
	v_mfma_f32_16x16x32_bf16 v[60:63], v[144:147], v[200:203], 0
	v_mfma_f32_16x16x32_bf16 v[60:63], v[148:151], v[210:213], v[60:63]
	v_mfma_f32_16x16x32_bf16 v[56:59], v[152:155], v[200:203], 0
	v_mfma_f32_16x16x32_bf16 v[56:59], v[166:169], v[210:213], v[56:59]
	v_mfma_f32_16x16x32_bf16 v[44:47], v[144:147], v[214:217], 0
	v_mfma_f32_16x16x32_bf16 v[44:47], v[148:151], v[218:221], v[44:47]
	v_mfma_f32_16x16x32_bf16 v[40:43], v[152:155], v[214:217], 0
	v_mfma_f32_16x16x32_bf16 v[40:43], v[166:169], v[218:221], v[40:43]
	v_mfma_f32_16x16x32_bf16 v[28:31], v[144:147], v[222:225], 0
	v_mfma_f32_16x16x32_bf16 v[28:31], v[148:151], v[226:229], v[28:31]
	v_mfma_f32_16x16x32_bf16 v[24:27], v[152:155], v[222:225], 0
	v_mfma_f32_16x16x32_bf16 v[24:27], v[166:169], v[226:229], v[24:27]
	v_mfma_f32_16x16x32_bf16 v[12:15], v[144:147], v[230:233], 0
	v_mfma_f32_16x16x32_bf16 v[12:15], v[148:151], v[234:237], v[12:15]
	v_mfma_f32_16x16x32_bf16 v[8:11], v[152:155], v[230:233], 0
	v_mfma_f32_16x16x32_bf16 v[8:11], v[166:169], v[234:237], v[8:11]
	v_mfma_f32_16x16x32_bf16 v[52:55], v[184:187], v[200:203], 0
	v_mfma_f32_16x16x32_bf16 v[52:55], v[188:191], v[210:213], v[52:55]
	v_mfma_f32_16x16x32_bf16 v[48:51], v[192:195], v[200:203], 0
	v_mfma_f32_16x16x32_bf16 v[48:51], v[196:199], v[210:213], v[48:51]
	v_mfma_f32_16x16x32_bf16 v[36:39], v[184:187], v[214:217], 0
	v_mfma_f32_16x16x32_bf16 v[36:39], v[188:191], v[218:221], v[36:39]
	v_mfma_f32_16x16x32_bf16 v[32:35], v[192:195], v[214:217], 0
	v_mfma_f32_16x16x32_bf16 v[32:35], v[196:199], v[218:221], v[32:35]
	v_mfma_f32_16x16x32_bf16 v[20:23], v[184:187], v[222:225], 0
	v_mfma_f32_16x16x32_bf16 v[20:23], v[188:191], v[226:229], v[20:23]
	v_mfma_f32_16x16x32_bf16 v[16:19], v[192:195], v[222:225], 0
	v_mfma_f32_16x16x32_bf16 v[16:19], v[196:199], v[226:229], v[16:19]
	v_mfma_f32_16x16x32_bf16 v[4:7], v[184:187], v[230:233], 0
	v_mfma_f32_16x16x32_bf16 v[4:7], v[188:191], v[234:237], v[4:7]
	s_setprio 3
	s_barrier
	v_mfma_f32_16x16x32_bf16 v[0:3], v[192:195], v[230:233], 0
	v_mfma_f32_16x16x32_bf16 v[0:3], v[196:199], v[234:237], v[0:3]
	s_setprio 0
	s_add_i32 s13, 0, 0x18000
	s_add_i32 s77, 0, 0x1c000
	v_add_u32_e32 v166, s13, v164
	v_add_u32_e32 v183, s77, v164
	ds_read_b128 v[144:147], v166
	ds_read_b128 v[148:151], v166 offset:1024
	ds_read_b128 v[152:155], v166 offset:2048
	ds_read_b128 v[166:169], v166 offset:3072
	ds_read_b128 v[184:187], v183
	ds_read_b128 v[188:191], v183 offset:1024
	ds_read_b128 v[192:195], v183 offset:2048
	ds_read_b128 v[196:199], v183 offset:3072
	s_add_u32 s2, s52, 0x40000
	s_addc_u32 s3, s53, 0
	s_mov_b32 m0, s60
	v_lshl_add_u64 v[242:243], s[2:3], 0, v[128:129]
	ds_read_b128 v[200:203], v165 offset:32768
	ds_read_b128 v[210:213], v165 offset:33792
	ds_read_b128 v[214:217], v165 offset:34816
	ds_read_b128 v[218:221], v165 offset:35840
	ds_read_b128 v[222:225], v165 offset:36864
	ds_read_b128 v[226:229], v165 offset:37888
	ds_read_b128 v[230:233], v165 offset:38912
	ds_read_b128 v[234:237], v165 offset:39936
	global_load_lds_dwordx4 v[242:243], off
	v_lshl_add_u64 v[242:243], s[2:3], 0, v[130:131]
	s_mov_b32 m0, s61
	s_nop 0
	global_load_lds_dwordx4 v[242:243], off
	s_waitcnt vmcnt(8)
	s_waitcnt lgkmcnt(0)
	s_setprio 1
	s_barrier
	v_mfma_f32_16x16x32_bf16 v[124:127], v[144:147], v[200:203], v[124:127]
	v_mfma_f32_16x16x32_bf16 v[124:127], v[148:151], v[210:213], v[124:127]
	v_mfma_f32_16x16x32_bf16 v[120:123], v[152:155], v[200:203], v[120:123]
	v_mfma_f32_16x16x32_bf16 v[120:123], v[166:169], v[210:213], v[120:123]
	v_mfma_f32_16x16x32_bf16 v[108:111], v[144:147], v[214:217], v[108:111]
	v_mfma_f32_16x16x32_bf16 v[108:111], v[148:151], v[218:221], v[108:111]
	v_mfma_f32_16x16x32_bf16 v[104:107], v[152:155], v[214:217], v[104:107]
	v_mfma_f32_16x16x32_bf16 v[104:107], v[166:169], v[218:221], v[104:107]
	v_mfma_f32_16x16x32_bf16 v[92:95], v[144:147], v[222:225], v[92:95]
	v_mfma_f32_16x16x32_bf16 v[92:95], v[148:151], v[226:229], v[92:95]
	v_mfma_f32_16x16x32_bf16 v[88:91], v[152:155], v[222:225], v[88:91]
	v_mfma_f32_16x16x32_bf16 v[88:91], v[166:169], v[226:229], v[88:91]
	v_mfma_f32_16x16x32_bf16 v[76:79], v[144:147], v[230:233], v[76:79]
	v_mfma_f32_16x16x32_bf16 v[76:79], v[148:151], v[234:237], v[76:79]
	v_mfma_f32_16x16x32_bf16 v[72:75], v[152:155], v[230:233], v[72:75]
	v_mfma_f32_16x16x32_bf16 v[72:75], v[166:169], v[234:237], v[72:75]
	v_mfma_f32_16x16x32_bf16 v[116:119], v[184:187], v[200:203], v[116:119]
	v_mfma_f32_16x16x32_bf16 v[116:119], v[188:191], v[210:213], v[116:119]
	v_mfma_f32_16x16x32_bf16 v[112:115], v[192:195], v[200:203], v[112:115]
	v_mfma_f32_16x16x32_bf16 v[112:115], v[196:199], v[210:213], v[112:115]
	v_mfma_f32_16x16x32_bf16 v[100:103], v[184:187], v[214:217], v[100:103]
	v_mfma_f32_16x16x32_bf16 v[100:103], v[188:191], v[218:221], v[100:103]
	v_mfma_f32_16x16x32_bf16 v[96:99], v[192:195], v[214:217], v[96:99]
	v_mfma_f32_16x16x32_bf16 v[96:99], v[196:199], v[218:221], v[96:99]
	v_mfma_f32_16x16x32_bf16 v[84:87], v[184:187], v[222:225], v[84:87]
	v_mfma_f32_16x16x32_bf16 v[84:87], v[188:191], v[226:229], v[84:87]
	v_mfma_f32_16x16x32_bf16 v[80:83], v[192:195], v[222:225], v[80:83]
	v_mfma_f32_16x16x32_bf16 v[80:83], v[196:199], v[226:229], v[80:83]
	v_mfma_f32_16x16x32_bf16 v[68:71], v[184:187], v[230:233], v[68:71]
	v_mfma_f32_16x16x32_bf16 v[68:71], v[188:191], v[234:237], v[68:71]
	s_setprio 3
	s_barrier
	v_mfma_f32_16x16x32_bf16 v[64:67], v[192:195], v[230:233], v[64:67]
	v_mfma_f32_16x16x32_bf16 v[64:67], v[196:199], v[234:237], v[64:67]
	s_setprio 0
	s_add_i32 s2, s13, s56
	v_lshl_add_u64 v[156:157], v[156:157], 0, s[82:83]
	s_mov_b32 m0, s2
	ds_read_b128 v[200:203], v165 offset:49152
	ds_read_b128 v[210:213], v165 offset:50176
	ds_read_b128 v[214:217], v165 offset:51200
	ds_read_b128 v[218:221], v165 offset:52224
	ds_read_b128 v[222:225], v165 offset:53248
	ds_read_b128 v[226:229], v165 offset:54272
	ds_read_b128 v[230:233], v165 offset:55296
	ds_read_b128 v[234:237], v165 offset:56320
	global_load_lds_dwordx4 v[156:157], off
	s_add_i32 m0, s2, 0x2000
	s_add_u32 s2, s10, 0x40080
	v_lshl_add_u64 v[156:157], v[170:171], 0, s[82:83]
	s_addc_u32 s3, s11, 0
	s_add_i32 s10, s77, s56
	global_load_lds_dwordx4 v[156:157], off
	v_lshl_add_u64 v[156:157], s[2:3], 0, v[174:175]
	s_mov_b32 m0, s10
	s_nop 0
	global_load_lds_dwordx4 v[156:157], off
	v_lshl_add_u64 v[156:157], s[2:3], 0, v[132:133]
	s_add_i32 m0, s10, 0x2000
	s_nop 0
	global_load_lds_dwordx4 v[156:157], off
	v_lshl_add_u64 v[156:157], v[238:239], 0, s[82:83]
	s_mov_b32 m0, s39
	s_nop 0
	global_load_lds_dwordx4 v[156:157], off
	v_lshl_add_u64 v[156:157], v[240:241], 0, s[82:83]
	s_mov_b32 m0, s46
	s_nop 0
	global_load_lds_dwordx4 v[156:157], off
	s_waitcnt vmcnt(8)
	s_waitcnt lgkmcnt(0)
	s_setprio 1
	s_barrier
	v_mfma_f32_16x16x32_bf16 v[60:63], v[144:147], v[200:203], v[60:63]
	v_mfma_f32_16x16x32_bf16 v[60:63], v[148:151], v[210:213], v[60:63]
	v_mfma_f32_16x16x32_bf16 v[56:59], v[152:155], v[200:203], v[56:59]
	v_mfma_f32_16x16x32_bf16 v[56:59], v[166:169], v[210:213], v[56:59]
	v_mfma_f32_16x16x32_bf16 v[44:47], v[144:147], v[214:217], v[44:47]
	v_mfma_f32_16x16x32_bf16 v[44:47], v[148:151], v[218:221], v[44:47]
	v_mfma_f32_16x16x32_bf16 v[40:43], v[152:155], v[214:217], v[40:43]
	v_mfma_f32_16x16x32_bf16 v[40:43], v[166:169], v[218:221], v[40:43]
	v_mfma_f32_16x16x32_bf16 v[28:31], v[144:147], v[222:225], v[28:31]
	v_mfma_f32_16x16x32_bf16 v[28:31], v[148:151], v[226:229], v[28:31]
	v_mfma_f32_16x16x32_bf16 v[24:27], v[152:155], v[222:225], v[24:27]
	v_mfma_f32_16x16x32_bf16 v[24:27], v[166:169], v[226:229], v[24:27]
	v_mfma_f32_16x16x32_bf16 v[12:15], v[144:147], v[230:233], v[12:15]
	v_mfma_f32_16x16x32_bf16 v[12:15], v[148:151], v[234:237], v[12:15]
	v_mfma_f32_16x16x32_bf16 v[8:11], v[152:155], v[230:233], v[8:11]
	v_mfma_f32_16x16x32_bf16 v[8:11], v[166:169], v[234:237], v[8:11]
	v_mfma_f32_16x16x32_bf16 v[52:55], v[184:187], v[200:203], v[52:55]
	v_mfma_f32_16x16x32_bf16 v[52:55], v[188:191], v[210:213], v[52:55]
	v_mfma_f32_16x16x32_bf16 v[48:51], v[192:195], v[200:203], v[48:51]
	v_mfma_f32_16x16x32_bf16 v[48:51], v[196:199], v[210:213], v[48:51]
	v_mfma_f32_16x16x32_bf16 v[36:39], v[184:187], v[214:217], v[36:39]
	v_mfma_f32_16x16x32_bf16 v[36:39], v[188:191], v[218:221], v[36:39]
	v_mfma_f32_16x16x32_bf16 v[32:35], v[192:195], v[214:217], v[32:35]
	v_mfma_f32_16x16x32_bf16 v[32:35], v[196:199], v[218:221], v[32:35]
	v_mfma_f32_16x16x32_bf16 v[20:23], v[184:187], v[222:225], v[20:23]
	v_mfma_f32_16x16x32_bf16 v[20:23], v[188:191], v[226:229], v[20:23]
	v_mfma_f32_16x16x32_bf16 v[16:19], v[192:195], v[222:225], v[16:19]
	v_mfma_f32_16x16x32_bf16 v[16:19], v[196:199], v[226:229], v[16:19]
	v_mfma_f32_16x16x32_bf16 v[4:7], v[184:187], v[230:233], v[4:7]
	v_mfma_f32_16x16x32_bf16 v[4:7], v[188:191], v[234:237], v[4:7]
	s_setprio 3
	s_barrier
	v_mfma_f32_16x16x32_bf16 v[0:3], v[192:195], v[230:233], v[0:3]
	v_mfma_f32_16x16x32_bf16 v[0:3], v[196:199], v[234:237], v[0:3]
	s_setprio 0
	s_add_i32 s12, s12, 2
	s_add_u32 vcc_lo, vcc_lo, 0x100
	s_addc_u32 vcc_hi, vcc_hi, 0
	s_add_u32 s8, s8, 0x100
	s_addc_u32 s9, s9, 0
	s_cmp_gt_u32 s12, 13
	s_cbranch_scc1 .Lexit_242
